# first-unit peel: the first unit of every GEMM phase also runs its first K iteration from a copy with SrcC=0 first-touch MFMAs (no 128-register zeroing block, no zeroing-block waits), no setprio
# baseline (speedup 1.0000x reference)
.LBB0_142:
	s_lshl_b32 s86, s85, 20
	s_and_b64 s[0:1], s[40:41], exec
	s_cselect_b32 s0, s86, s4
	s_lshl_b32 s87, s84, 20
	s_and_b64 s[6:7], s[40:41], exec
	s_cselect_b32 s1, s87, s5
	s_add_i32 s4, s4, 0x84000
	s_add_i32 s5, s5, 0x8000
	s_mov_b32 s6, -2
	s_cmp_eq_u32 s82, 1
	s_cbranch_scc0 .Lpeel_p1
	v_add_u32_e32 v28, 0x10000, v83
	v_add_u32_e32 v80, 0x14000, v83
	ds_read_b128 v[16:19], v28
	ds_read_b128 v[20:23], v28 offset:1024
	ds_read_b128 v[24:27], v28 offset:2048
	ds_read_b128 v[28:31], v28 offset:3072
	ds_read_b128 v[152:155], v80
	ds_read_b128 v[160:163], v80 offset:1024
	ds_read_b128 v[168:171], v80 offset:2048
	ds_read_b128 v[176:179], v80 offset:3072
	s_add_i32 s7, s4, 0xfff84000
	s_cmp_eq_u32 s6, 28
	s_cselect_b32 s17, s0, s7
	s_cselect_b32 s16, s1, s5
	s_or_b32 s7, s17, 0x4000
	ds_read_b128 v[192:195], v245
	ds_read_b128 v[196:199], v245 offset:1024
	ds_read_b128 v[200:203], v245 offset:2048
	ds_read_b128 v[204:207], v245 offset:3072
	ds_read_b128 v[220:223], v245 offset:4096
	ds_read_b128 v[224:227], v245 offset:5120
	ds_read_b128 v[228:231], v245 offset:6144
	ds_read_b128 v[246:249], v245 offset:7168
	s_mov_b32 m0, s79
	s_nop 0
	buffer_load_dwordx4 v242, s[24:27], s4 offen lds
	s_nop 0
	s_mov_b32 m0, s83
	s_nop 0
	buffer_load_dwordx4 v243, s[24:27], s4 offen lds
	s_waitcnt vmcnt(8)
	s_waitcnt lgkmcnt(0)
	s_barrier
	s_waitcnt lgkmcnt(7)
	v_mfma_f32_16x16x32_bf16 v[180:183], v[16:19], v[192:195], 0
	v_mfma_f32_16x16x32_bf16 v[164:167], v[24:27], v[192:195], 0
	s_waitcnt lgkmcnt(5)
	v_mfma_f32_16x16x32_bf16 v[148:151], v[16:19], v[200:203], 0
	v_mfma_f32_16x16x32_bf16 v[140:143], v[24:27], v[200:203], 0
	s_waitcnt lgkmcnt(3)
	v_mfma_f32_16x16x32_bf16 v[132:135], v[16:19], v[220:223], 0
	v_mfma_f32_16x16x32_bf16 v[124:127], v[24:27], v[220:223], 0
	s_waitcnt lgkmcnt(1)
	v_mfma_f32_16x16x32_bf16 v[116:119], v[16:19], v[228:231], 0
	v_mfma_f32_16x16x32_bf16 v[108:111], v[24:27], v[228:231], 0
	v_mfma_f32_16x16x32_bf16 v[180:183], v[20:23], v[196:199], v[180:183]
	v_mfma_f32_16x16x32_bf16 v[164:167], v[28:31], v[196:199], v[164:167]
	v_mfma_f32_16x16x32_bf16 v[148:151], v[20:23], v[204:207], v[148:151]
	v_mfma_f32_16x16x32_bf16 v[140:143], v[28:31], v[204:207], v[140:143]
	v_mfma_f32_16x16x32_bf16 v[132:135], v[20:23], v[224:227], v[132:135]
	v_mfma_f32_16x16x32_bf16 v[124:127], v[28:31], v[224:227], v[124:127]
	s_waitcnt lgkmcnt(0)
	v_mfma_f32_16x16x32_bf16 v[116:119], v[20:23], v[246:249], v[116:119]
	v_mfma_f32_16x16x32_bf16 v[108:111], v[28:31], v[246:249], v[108:111]
	v_mfma_f32_16x16x32_bf16 v[172:175], v[152:155], v[192:195], 0
	v_mfma_f32_16x16x32_bf16 v[156:159], v[168:171], v[192:195], 0
	v_mfma_f32_16x16x32_bf16 v[144:147], v[152:155], v[200:203], 0
	v_mfma_f32_16x16x32_bf16 v[136:139], v[168:171], v[200:203], 0
	v_mfma_f32_16x16x32_bf16 v[128:131], v[152:155], v[220:223], 0
	v_mfma_f32_16x16x32_bf16 v[120:123], v[168:171], v[220:223], 0
	v_mfma_f32_16x16x32_bf16 v[112:115], v[152:155], v[228:231], 0
	v_mfma_f32_16x16x32_bf16 v[104:107], v[168:171], v[228:231], 0
	v_mfma_f32_16x16x32_bf16 v[172:175], v[160:163], v[196:199], v[172:175]
	v_mfma_f32_16x16x32_bf16 v[156:159], v[176:179], v[196:199], v[156:159]
	v_mfma_f32_16x16x32_bf16 v[144:147], v[160:163], v[204:207], v[144:147]
	v_mfma_f32_16x16x32_bf16 v[136:139], v[176:179], v[204:207], v[136:139]
	v_mfma_f32_16x16x32_bf16 v[128:131], v[160:163], v[224:227], v[128:131]
	v_mfma_f32_16x16x32_bf16 v[120:123], v[176:179], v[224:227], v[120:123]
	v_mfma_f32_16x16x32_bf16 v[112:115], v[160:163], v[246:249], v[112:115]
	v_mfma_f32_16x16x32_bf16 v[104:107], v[176:179], v[246:249], v[104:107]
	s_barrier
	ds_read_b128 v[192:195], v245 offset:16384
	ds_read_b128 v[196:199], v245 offset:17408
	ds_read_b128 v[200:203], v245 offset:18432
	ds_read_b128 v[204:207], v245 offset:19456
	ds_read_b128 v[220:223], v245 offset:20480
	ds_read_b128 v[224:227], v245 offset:21504
	ds_read_b128 v[228:231], v245 offset:22528
	ds_read_b128 v[246:249], v245 offset:23552
	s_mov_b32 m0, s51
	s_nop 0
	buffer_load_dwordx4 v242, s[56:59], s16 offen lds
	s_add_i32 s18, s16, 0x80000
	s_mov_b32 m0, s52
	s_nop 0
	buffer_load_dwordx4 v243, s[56:59], s16 offen lds
	s_nop 0
	s_mov_b32 m0, s53
	s_nop 0
	buffer_load_dwordx4 v242, s[56:59], s18 offen lds
	s_nop 0
	s_mov_b32 m0, s55
	s_nop 0
	buffer_load_dwordx4 v243, s[56:59], s18 offen lds
	s_nop 0
	s_mov_b32 m0, s31
	s_nop 0
	buffer_load_dwordx4 v242, s[24:27], s17 offen lds
	s_nop 0
	s_mov_b32 m0, s68
	s_nop 0
	buffer_load_dwordx4 v243, s[24:27], s17 offen lds
	s_waitcnt vmcnt(8)
	s_waitcnt lgkmcnt(0)
	s_barrier
	s_waitcnt lgkmcnt(7)
	v_mfma_f32_16x16x32_bf16 v[76:79], v[16:19], v[192:195], 0
	v_mfma_f32_16x16x32_bf16 v[68:71], v[24:27], v[192:195], 0
	s_waitcnt lgkmcnt(5)
	v_mfma_f32_16x16x32_bf16 v[60:63], v[16:19], v[200:203], 0
	v_mfma_f32_16x16x32_bf16 v[52:55], v[24:27], v[200:203], 0
	s_waitcnt lgkmcnt(3)
	v_mfma_f32_16x16x32_bf16 v[44:47], v[16:19], v[220:223], 0
	v_mfma_f32_16x16x32_bf16 v[36:39], v[24:27], v[220:223], 0
	s_waitcnt lgkmcnt(1)
	v_mfma_f32_16x16x32_bf16 v[12:15], v[16:19], v[228:231], 0
	v_mfma_f32_16x16x32_bf16 v[4:7], v[24:27], v[228:231], 0
	v_mfma_f32_16x16x32_bf16 v[76:79], v[20:23], v[196:199], v[76:79]
	v_mfma_f32_16x16x32_bf16 v[68:71], v[28:31], v[196:199], v[68:71]
	v_mfma_f32_16x16x32_bf16 v[60:63], v[20:23], v[204:207], v[60:63]
	v_mfma_f32_16x16x32_bf16 v[52:55], v[28:31], v[204:207], v[52:55]
	v_mfma_f32_16x16x32_bf16 v[44:47], v[20:23], v[224:227], v[44:47]
	v_mfma_f32_16x16x32_bf16 v[36:39], v[28:31], v[224:227], v[36:39]
	s_waitcnt lgkmcnt(0)
	v_mfma_f32_16x16x32_bf16 v[12:15], v[20:23], v[246:249], v[12:15]
	v_mfma_f32_16x16x32_bf16 v[4:7], v[28:31], v[246:249], v[4:7]
	v_mfma_f32_16x16x32_bf16 v[40:43], v[152:155], v[220:223], 0
	v_mfma_f32_16x16x32_bf16 v[32:35], v[168:171], v[220:223], 0
	v_mfma_f32_16x16x32_bf16 v[8:11], v[152:155], v[228:231], 0
	v_mfma_f32_16x16x32_bf16 v[0:3], v[168:171], v[228:231], 0
	v_mfma_f32_16x16x32_bf16 v[16:19], v[152:155], v[192:195], 0
	v_mfma_f32_16x16x32_bf16 v[20:23], v[168:171], v[192:195], 0
	v_mfma_f32_16x16x32_bf16 v[24:27], v[152:155], v[200:203], 0
	v_mfma_f32_16x16x32_bf16 v[28:31], v[168:171], v[200:203], 0
	v_mfma_f32_16x16x32_bf16 v[40:43], v[160:163], v[224:227], v[40:43]
	v_mfma_f32_16x16x32_bf16 v[32:35], v[176:179], v[224:227], v[32:35]
	v_mfma_f32_16x16x32_bf16 v[8:11], v[160:163], v[246:249], v[8:11]
	v_mfma_f32_16x16x32_bf16 v[0:3], v[176:179], v[246:249], v[0:3]
	v_mfma_f32_16x16x32_bf16 v[16:19], v[160:163], v[196:199], v[16:19]
	v_mfma_f32_16x16x32_bf16 v[20:23], v[176:179], v[196:199], v[20:23]
	v_mfma_f32_16x16x32_bf16 v[24:27], v[160:163], v[204:207], v[24:27]
	v_mfma_f32_16x16x32_bf16 v[28:31], v[176:179], v[204:207], v[28:31]
	s_barrier
	v_add_u32_e32 v72, 0x18000, v83
	v_add_u32_e32 v80, 0x1c000, v83
	ds_read_b128 v[48:51], v72
	ds_read_b128 v[56:59], v72 offset:1024
	ds_read_b128 v[64:67], v72 offset:2048
	ds_read_b128 v[72:75], v72 offset:3072
	ds_read_b128 v[152:155], v80
	ds_read_b128 v[160:163], v80 offset:1024
	ds_read_b128 v[168:171], v80 offset:2048
	ds_read_b128 v[176:179], v80 offset:3072
	ds_read_b128 v[192:195], v245 offset:32768
	ds_read_b128 v[196:199], v245 offset:33792
	ds_read_b128 v[200:203], v245 offset:34816
	ds_read_b128 v[204:207], v245 offset:35840
	ds_read_b128 v[220:223], v245 offset:36864
	ds_read_b128 v[224:227], v245 offset:37888
	ds_read_b128 v[228:231], v245 offset:38912
	ds_read_b128 v[246:249], v245 offset:39936
	s_add_i32 s17, s17, 0x80000
	s_mov_b32 m0, s69
	s_nop 0
	buffer_load_dwordx4 v242, s[24:27], s17 offen lds
	s_nop 0
	s_mov_b32 m0, s70
	s_nop 0
	buffer_load_dwordx4 v243, s[24:27], s17 offen lds
	s_waitcnt vmcnt(8)
	s_waitcnt lgkmcnt(0)
	s_barrier
	s_waitcnt lgkmcnt(7)
	v_mfma_f32_16x16x32_bf16 v[180:183], v[48:51], v[192:195], v[180:183]
	v_mfma_f32_16x16x32_bf16 v[164:167], v[64:67], v[192:195], v[164:167]
	s_waitcnt lgkmcnt(5)
	v_mfma_f32_16x16x32_bf16 v[148:151], v[48:51], v[200:203], v[148:151]
	v_mfma_f32_16x16x32_bf16 v[140:143], v[64:67], v[200:203], v[140:143]
	s_waitcnt lgkmcnt(3)
	v_mfma_f32_16x16x32_bf16 v[132:135], v[48:51], v[220:223], v[132:135]
	v_mfma_f32_16x16x32_bf16 v[124:127], v[64:67], v[220:223], v[124:127]
	s_waitcnt lgkmcnt(1)
	v_mfma_f32_16x16x32_bf16 v[116:119], v[48:51], v[228:231], v[116:119]
	v_mfma_f32_16x16x32_bf16 v[108:111], v[64:67], v[228:231], v[108:111]
	v_mfma_f32_16x16x32_bf16 v[180:183], v[56:59], v[196:199], v[180:183]
	v_mfma_f32_16x16x32_bf16 v[164:167], v[72:75], v[196:199], v[164:167]
	v_mfma_f32_16x16x32_bf16 v[148:151], v[56:59], v[204:207], v[148:151]
	v_mfma_f32_16x16x32_bf16 v[140:143], v[72:75], v[204:207], v[140:143]
	v_mfma_f32_16x16x32_bf16 v[132:135], v[56:59], v[224:227], v[132:135]
	v_mfma_f32_16x16x32_bf16 v[124:127], v[72:75], v[224:227], v[124:127]
	s_waitcnt lgkmcnt(0)
	v_mfma_f32_16x16x32_bf16 v[116:119], v[56:59], v[246:249], v[116:119]
	v_mfma_f32_16x16x32_bf16 v[108:111], v[72:75], v[246:249], v[108:111]
	v_mfma_f32_16x16x32_bf16 v[172:175], v[152:155], v[192:195], v[172:175]
	v_mfma_f32_16x16x32_bf16 v[156:159], v[168:171], v[192:195], v[156:159]
	v_mfma_f32_16x16x32_bf16 v[144:147], v[152:155], v[200:203], v[144:147]
	v_mfma_f32_16x16x32_bf16 v[136:139], v[168:171], v[200:203], v[136:139]
	v_mfma_f32_16x16x32_bf16 v[128:131], v[152:155], v[220:223], v[128:131]
	v_mfma_f32_16x16x32_bf16 v[120:123], v[168:171], v[220:223], v[120:123]
	v_mfma_f32_16x16x32_bf16 v[112:115], v[152:155], v[228:231], v[112:115]
	v_mfma_f32_16x16x32_bf16 v[104:107], v[168:171], v[228:231], v[104:107]
	v_mfma_f32_16x16x32_bf16 v[172:175], v[160:163], v[196:199], v[172:175]
	v_mfma_f32_16x16x32_bf16 v[156:159], v[176:179], v[196:199], v[156:159]
	v_mfma_f32_16x16x32_bf16 v[144:147], v[160:163], v[204:207], v[144:147]
	v_mfma_f32_16x16x32_bf16 v[136:139], v[176:179], v[204:207], v[136:139]
	v_mfma_f32_16x16x32_bf16 v[128:131], v[160:163], v[224:227], v[128:131]
	v_mfma_f32_16x16x32_bf16 v[120:123], v[176:179], v[224:227], v[120:123]
	v_mfma_f32_16x16x32_bf16 v[112:115], v[160:163], v[246:249], v[112:115]
	v_mfma_f32_16x16x32_bf16 v[104:107], v[176:179], v[246:249], v[104:107]
	s_barrier
	ds_read_b128 v[192:195], v245 offset:49152
	ds_read_b128 v[196:199], v245 offset:50176
	ds_read_b128 v[200:203], v245 offset:51200
	ds_read_b128 v[204:207], v245 offset:52224
	ds_read_b128 v[220:223], v245 offset:53248
	ds_read_b128 v[224:227], v245 offset:54272
	ds_read_b128 v[228:231], v245 offset:55296
	ds_read_b128 v[246:249], v245 offset:56320
	s_or_b32 s17, s16, 0x4000
	s_mov_b32 m0, s73
	s_nop 0
	buffer_load_dwordx4 v242, s[56:59], s17 offen lds
	s_add_i32 s16, s16, 0x84000
	s_mov_b32 m0, s74
	s_nop 0
	buffer_load_dwordx4 v243, s[56:59], s17 offen lds
	s_nop 0
	s_mov_b32 m0, s77
	s_nop 0
	buffer_load_dwordx4 v242, s[56:59], s16 offen lds
	s_nop 0
	s_mov_b32 m0, s78
	s_nop 0
	buffer_load_dwordx4 v243, s[56:59], s16 offen lds
	s_nop 0
	s_mov_b32 m0, s75
	s_nop 0
	buffer_load_dwordx4 v242, s[24:27], s7 offen lds
	s_nop 0
	s_mov_b32 m0, s76
	s_nop 0
	buffer_load_dwordx4 v243, s[24:27], s7 offen lds
	s_waitcnt vmcnt(8)
	s_waitcnt lgkmcnt(0)
	s_barrier
	s_waitcnt lgkmcnt(7)
	v_mfma_f32_16x16x32_bf16 v[76:79], v[48:51], v[192:195], v[76:79]
	v_mfma_f32_16x16x32_bf16 v[68:71], v[64:67], v[192:195], v[68:71]
	s_waitcnt lgkmcnt(5)
	v_mfma_f32_16x16x32_bf16 v[60:63], v[48:51], v[200:203], v[60:63]
	v_mfma_f32_16x16x32_bf16 v[52:55], v[64:67], v[200:203], v[52:55]
	s_waitcnt lgkmcnt(3)
	v_mfma_f32_16x16x32_bf16 v[44:47], v[48:51], v[220:223], v[44:47]
	v_mfma_f32_16x16x32_bf16 v[36:39], v[64:67], v[220:223], v[36:39]
	s_waitcnt lgkmcnt(1)
	v_mfma_f32_16x16x32_bf16 v[12:15], v[48:51], v[228:231], v[12:15]
	v_mfma_f32_16x16x32_bf16 v[4:7], v[64:67], v[228:231], v[4:7]
	v_mfma_f32_16x16x32_bf16 v[76:79], v[56:59], v[196:199], v[76:79]
	v_mfma_f32_16x16x32_bf16 v[68:71], v[72:75], v[196:199], v[68:71]
	v_mfma_f32_16x16x32_bf16 v[60:63], v[56:59], v[204:207], v[60:63]
	v_mfma_f32_16x16x32_bf16 v[52:55], v[72:75], v[204:207], v[52:55]
	v_mfma_f32_16x16x32_bf16 v[44:47], v[56:59], v[224:227], v[44:47]
	v_mfma_f32_16x16x32_bf16 v[36:39], v[72:75], v[224:227], v[36:39]
	s_waitcnt lgkmcnt(0)
	v_mfma_f32_16x16x32_bf16 v[12:15], v[56:59], v[246:249], v[12:15]
	v_mfma_f32_16x16x32_bf16 v[4:7], v[72:75], v[246:249], v[4:7]
	v_mfma_f32_16x16x32_bf16 v[16:19], v[152:155], v[192:195], v[16:19]
	v_mfma_f32_16x16x32_bf16 v[72:75], v[160:163], v[196:199], v[16:19]
	v_mfma_f32_16x16x32_bf16 v[16:19], v[168:171], v[192:195], v[20:23]
	v_mfma_f32_16x16x32_bf16 v[64:67], v[176:179], v[196:199], v[16:19]
	v_mfma_f32_16x16x32_bf16 v[16:19], v[152:155], v[200:203], v[24:27]
	v_mfma_f32_16x16x32_bf16 v[56:59], v[160:163], v[204:207], v[16:19]
	v_mfma_f32_16x16x32_bf16 v[16:19], v[168:171], v[200:203], v[28:31]
	v_mfma_f32_16x16x32_bf16 v[48:51], v[176:179], v[204:207], v[16:19]
	v_mfma_f32_16x16x32_bf16 v[16:19], v[152:155], v[220:223], v[40:43]
	v_mfma_f32_16x16x32_bf16 v[40:43], v[160:163], v[224:227], v[16:19]
	v_mfma_f32_16x16x32_bf16 v[16:19], v[168:171], v[220:223], v[32:35]
	v_mfma_f32_16x16x32_bf16 v[8:11], v[152:155], v[228:231], v[8:11]
	v_mfma_f32_16x16x32_bf16 v[0:3], v[168:171], v[228:231], v[0:3]
	v_mfma_f32_16x16x32_bf16 v[32:35], v[176:179], v[224:227], v[16:19]
	v_mfma_f32_16x16x32_bf16 v[8:11], v[160:163], v[246:249], v[8:11]
	v_mfma_f32_16x16x32_bf16 v[0:3], v[176:179], v[246:249], v[0:3]
	s_barrier
	s_add_i32 s6, s6, 2
	s_add_i32 s4, s4, 0x8000
	s_add_i32 s5, s5, 0x8000
	s_branch .LBB0_143

.LBB0_690:
	s_lshl_b32 s94, s92, 20
	s_and_b64 s[6:7], s[40:41], exec
	s_cselect_b32 s6, s94, s8
	s_lshl_b32 s95, s93, 20
	s_and_b64 s[10:11], s[40:41], exec
	s_cselect_b32 s7, s95, s9
	s_add_i32 s8, s8, 0x84000
	s_add_i32 s9, s9, 0x8000
	s_mov_b32 s10, -2
	s_cmp_eq_u32 s90, 1
	s_cbranch_scc0 .Lpeel_p4
	v_add_u32_e32 v156, 0x10000, v222
	v_add_u32_e32 v180, 0x14000, v222
	ds_read_b128 v[128:131], v156
	ds_read_b128 v[140:143], v156 offset:1024
	ds_read_b128 v[152:155], v156 offset:2048
	ds_read_b128 v[156:159], v156 offset:3072
	ds_read_b128 v[168:171], v180
	ds_read_b128 v[172:175], v180 offset:1024
	ds_read_b128 v[176:179], v180 offset:2048
	ds_read_b128 v[180:183], v180 offset:3072
	s_add_i32 s11, s8, 0xfff84000
	s_cmp_eq_u32 s10, 28
	s_cselect_b32 s13, s6, s11
	s_cselect_b32 s12, s7, s9
	s_or_b32 s11, s13, 0x4000
	ds_read_b128 v[184:187], v223
	ds_read_b128 v[188:191], v223 offset:1024
	ds_read_b128 v[192:195], v223 offset:2048
	ds_read_b128 v[196:199], v223 offset:3072
	ds_read_b128 v[200:203], v223 offset:4096
	ds_read_b128 v[204:207], v223 offset:5120
	ds_read_b128 v[224:227], v223 offset:6144
	ds_read_b128 v[228:231], v223 offset:7168
	s_mov_b32 m0, s89
	s_nop 0
	buffer_load_dwordx4 v220, s[64:67], s8 offen lds
	s_nop 0
	s_mov_b32 m0, s91
	s_nop 0
	buffer_load_dwordx4 v221, s[64:67], s8 offen lds
	s_waitcnt vmcnt(8)
	s_waitcnt lgkmcnt(0)
	s_barrier
	s_waitcnt lgkmcnt(7)
	v_mfma_f32_16x16x32_bf16 v[164:167], v[128:131], v[184:187], 0
	v_mfma_f32_16x16x32_bf16 v[160:163], v[152:155], v[184:187], 0
	s_waitcnt lgkmcnt(5)
	v_mfma_f32_16x16x32_bf16 v[136:139], v[128:131], v[192:195], 0
	v_mfma_f32_16x16x32_bf16 v[132:135], v[152:155], v[192:195], 0
	s_waitcnt lgkmcnt(3)
	v_mfma_f32_16x16x32_bf16 v[116:119], v[128:131], v[200:203], 0
	v_mfma_f32_16x16x32_bf16 v[112:115], v[152:155], v[200:203], 0
	s_waitcnt lgkmcnt(1)
	v_mfma_f32_16x16x32_bf16 v[76:79], v[128:131], v[224:227], 0
	v_mfma_f32_16x16x32_bf16 v[72:75], v[152:155], v[224:227], 0
	v_mfma_f32_16x16x32_bf16 v[164:167], v[140:143], v[188:191], v[164:167]
	v_mfma_f32_16x16x32_bf16 v[160:163], v[156:159], v[188:191], v[160:163]
	v_mfma_f32_16x16x32_bf16 v[136:139], v[140:143], v[196:199], v[136:139]
	v_mfma_f32_16x16x32_bf16 v[132:135], v[156:159], v[196:199], v[132:135]
	v_mfma_f32_16x16x32_bf16 v[116:119], v[140:143], v[204:207], v[116:119]
	v_mfma_f32_16x16x32_bf16 v[112:115], v[156:159], v[204:207], v[112:115]
	s_waitcnt lgkmcnt(0)
	v_mfma_f32_16x16x32_bf16 v[76:79], v[140:143], v[228:231], v[76:79]
	v_mfma_f32_16x16x32_bf16 v[72:75], v[156:159], v[228:231], v[72:75]
	v_mfma_f32_16x16x32_bf16 v[148:151], v[168:171], v[184:187], 0
	v_mfma_f32_16x16x32_bf16 v[144:147], v[176:179], v[184:187], 0
	v_mfma_f32_16x16x32_bf16 v[124:127], v[168:171], v[192:195], 0
	v_mfma_f32_16x16x32_bf16 v[120:123], v[176:179], v[192:195], 0
	v_mfma_f32_16x16x32_bf16 v[108:111], v[168:171], v[200:203], 0
	v_mfma_f32_16x16x32_bf16 v[104:107], v[176:179], v[200:203], 0
	v_mfma_f32_16x16x32_bf16 v[68:71], v[168:171], v[224:227], 0
	v_mfma_f32_16x16x32_bf16 v[64:67], v[176:179], v[224:227], 0
	v_mfma_f32_16x16x32_bf16 v[148:151], v[172:175], v[188:191], v[148:151]
	v_mfma_f32_16x16x32_bf16 v[144:147], v[180:183], v[188:191], v[144:147]
	v_mfma_f32_16x16x32_bf16 v[124:127], v[172:175], v[196:199], v[124:127]
	v_mfma_f32_16x16x32_bf16 v[120:123], v[180:183], v[196:199], v[120:123]
	v_mfma_f32_16x16x32_bf16 v[108:111], v[172:175], v[204:207], v[108:111]
	v_mfma_f32_16x16x32_bf16 v[104:107], v[180:183], v[204:207], v[104:107]
	v_mfma_f32_16x16x32_bf16 v[68:71], v[172:175], v[228:231], v[68:71]
	v_mfma_f32_16x16x32_bf16 v[64:67], v[180:183], v[228:231], v[64:67]
	s_barrier
	ds_read_b128 v[184:187], v223 offset:16384
	ds_read_b128 v[188:191], v223 offset:17408
	ds_read_b128 v[192:195], v223 offset:18432
	ds_read_b128 v[196:199], v223 offset:19456
	ds_read_b128 v[200:203], v223 offset:20480
	ds_read_b128 v[204:207], v223 offset:21504
	ds_read_b128 v[224:227], v223 offset:22528
	ds_read_b128 v[228:231], v223 offset:23552
	s_mov_b32 m0, s55
	s_nop 0
	buffer_load_dwordx4 v220, s[48:51], s12 offen lds
	s_add_i32 s14, s12, 0x80000
	s_mov_b32 m0, s76
	s_nop 0
	buffer_load_dwordx4 v221, s[48:51], s12 offen lds
	s_nop 0
	s_mov_b32 m0, s77
	s_nop 0
	buffer_load_dwordx4 v220, s[48:51], s14 offen lds
	s_nop 0
	s_mov_b32 m0, s78
	s_nop 0
	buffer_load_dwordx4 v221, s[48:51], s14 offen lds
	s_nop 0
	s_mov_b32 m0, s31
	s_nop 0
	buffer_load_dwordx4 v220, s[64:67], s13 offen lds
	s_nop 0
	s_mov_b32 m0, s79
	s_nop 0
	buffer_load_dwordx4 v221, s[64:67], s13 offen lds
	s_waitcnt vmcnt(8)
	s_waitcnt lgkmcnt(0)
	s_barrier
	s_waitcnt lgkmcnt(7)
	v_mfma_f32_16x16x32_bf16 v[60:63], v[128:131], v[184:187], 0
	v_mfma_f32_16x16x32_bf16 v[56:59], v[152:155], v[184:187], 0
	s_waitcnt lgkmcnt(5)
	v_mfma_f32_16x16x32_bf16 v[44:47], v[128:131], v[192:195], 0
	v_mfma_f32_16x16x32_bf16 v[40:43], v[152:155], v[192:195], 0
	s_waitcnt lgkmcnt(3)
	v_mfma_f32_16x16x32_bf16 v[28:31], v[128:131], v[200:203], 0
	v_mfma_f32_16x16x32_bf16 v[24:27], v[152:155], v[200:203], 0
	s_waitcnt lgkmcnt(1)
	v_mfma_f32_16x16x32_bf16 v[12:15], v[128:131], v[224:227], 0
	v_mfma_f32_16x16x32_bf16 v[8:11], v[152:155], v[224:227], 0
	v_mfma_f32_16x16x32_bf16 v[60:63], v[140:143], v[188:191], v[60:63]
	v_mfma_f32_16x16x32_bf16 v[56:59], v[156:159], v[188:191], v[56:59]
	v_mfma_f32_16x16x32_bf16 v[44:47], v[140:143], v[196:199], v[44:47]
	v_mfma_f32_16x16x32_bf16 v[40:43], v[156:159], v[196:199], v[40:43]
	v_mfma_f32_16x16x32_bf16 v[28:31], v[140:143], v[204:207], v[28:31]
	v_mfma_f32_16x16x32_bf16 v[24:27], v[156:159], v[204:207], v[24:27]
	s_waitcnt lgkmcnt(0)
	v_mfma_f32_16x16x32_bf16 v[12:15], v[140:143], v[228:231], v[12:15]
	v_mfma_f32_16x16x32_bf16 v[8:11], v[156:159], v[228:231], v[8:11]
	v_mfma_f32_16x16x32_bf16 v[52:55], v[168:171], v[184:187], 0
	v_mfma_f32_16x16x32_bf16 v[48:51], v[176:179], v[184:187], 0
	v_mfma_f32_16x16x32_bf16 v[36:39], v[168:171], v[192:195], 0
	v_mfma_f32_16x16x32_bf16 v[32:35], v[176:179], v[192:195], 0
	v_mfma_f32_16x16x32_bf16 v[20:23], v[168:171], v[200:203], 0
	v_mfma_f32_16x16x32_bf16 v[16:19], v[176:179], v[200:203], 0
	v_mfma_f32_16x16x32_bf16 v[4:7], v[168:171], v[224:227], 0
	v_mfma_f32_16x16x32_bf16 v[0:3], v[176:179], v[224:227], 0
	v_mfma_f32_16x16x32_bf16 v[52:55], v[172:175], v[188:191], v[52:55]
	v_mfma_f32_16x16x32_bf16 v[48:51], v[180:183], v[188:191], v[48:51]
	v_mfma_f32_16x16x32_bf16 v[36:39], v[172:175], v[196:199], v[36:39]
	v_mfma_f32_16x16x32_bf16 v[32:35], v[180:183], v[196:199], v[32:35]
	v_mfma_f32_16x16x32_bf16 v[20:23], v[172:175], v[204:207], v[20:23]
	v_mfma_f32_16x16x32_bf16 v[16:19], v[180:183], v[204:207], v[16:19]
	v_mfma_f32_16x16x32_bf16 v[4:7], v[172:175], v[228:231], v[4:7]
	v_mfma_f32_16x16x32_bf16 v[0:3], v[180:183], v[228:231], v[0:3]
	s_barrier
	v_add_u32_e32 v156, 0x18000, v222
	v_add_u32_e32 v180, 0x1c000, v222
	ds_read_b128 v[128:131], v156
	ds_read_b128 v[140:143], v156 offset:1024
	ds_read_b128 v[152:155], v156 offset:2048
	ds_read_b128 v[156:159], v156 offset:3072
	ds_read_b128 v[168:171], v180
	ds_read_b128 v[172:175], v180 offset:1024
	ds_read_b128 v[176:179], v180 offset:2048
	ds_read_b128 v[180:183], v180 offset:3072
	ds_read_b128 v[184:187], v223 offset:32768
	ds_read_b128 v[188:191], v223 offset:33792
	ds_read_b128 v[192:195], v223 offset:34816
	ds_read_b128 v[196:199], v223 offset:35840
	ds_read_b128 v[200:203], v223 offset:36864
	ds_read_b128 v[204:207], v223 offset:37888
	ds_read_b128 v[224:227], v223 offset:38912
	ds_read_b128 v[228:231], v223 offset:39936
	s_add_i32 s13, s13, 0x80000
	s_mov_b32 m0, s82
	s_nop 0
	buffer_load_dwordx4 v220, s[64:67], s13 offen lds
	s_nop 0
	s_mov_b32 m0, s83
	s_nop 0
	buffer_load_dwordx4 v221, s[64:67], s13 offen lds
	s_waitcnt vmcnt(8)
	s_waitcnt lgkmcnt(0)
	s_barrier
	s_waitcnt lgkmcnt(7)
	v_mfma_f32_16x16x32_bf16 v[164:167], v[128:131], v[184:187], v[164:167]
	v_mfma_f32_16x16x32_bf16 v[160:163], v[152:155], v[184:187], v[160:163]
	s_waitcnt lgkmcnt(5)
	v_mfma_f32_16x16x32_bf16 v[136:139], v[128:131], v[192:195], v[136:139]
	v_mfma_f32_16x16x32_bf16 v[132:135], v[152:155], v[192:195], v[132:135]
	s_waitcnt lgkmcnt(3)
	v_mfma_f32_16x16x32_bf16 v[116:119], v[128:131], v[200:203], v[116:119]
	v_mfma_f32_16x16x32_bf16 v[112:115], v[152:155], v[200:203], v[112:115]
	s_waitcnt lgkmcnt(1)
	v_mfma_f32_16x16x32_bf16 v[76:79], v[128:131], v[224:227], v[76:79]
	v_mfma_f32_16x16x32_bf16 v[72:75], v[152:155], v[224:227], v[72:75]
	v_mfma_f32_16x16x32_bf16 v[164:167], v[140:143], v[188:191], v[164:167]
	v_mfma_f32_16x16x32_bf16 v[160:163], v[156:159], v[188:191], v[160:163]
	v_mfma_f32_16x16x32_bf16 v[136:139], v[140:143], v[196:199], v[136:139]
	v_mfma_f32_16x16x32_bf16 v[132:135], v[156:159], v[196:199], v[132:135]
	v_mfma_f32_16x16x32_bf16 v[116:119], v[140:143], v[204:207], v[116:119]
	v_mfma_f32_16x16x32_bf16 v[112:115], v[156:159], v[204:207], v[112:115]
	s_waitcnt lgkmcnt(0)
	v_mfma_f32_16x16x32_bf16 v[76:79], v[140:143], v[228:231], v[76:79]
	v_mfma_f32_16x16x32_bf16 v[72:75], v[156:159], v[228:231], v[72:75]
	v_mfma_f32_16x16x32_bf16 v[148:151], v[168:171], v[184:187], v[148:151]
	v_mfma_f32_16x16x32_bf16 v[144:147], v[176:179], v[184:187], v[144:147]
	v_mfma_f32_16x16x32_bf16 v[124:127], v[168:171], v[192:195], v[124:127]
	v_mfma_f32_16x16x32_bf16 v[120:123], v[176:179], v[192:195], v[120:123]
	v_mfma_f32_16x16x32_bf16 v[108:111], v[168:171], v[200:203], v[108:111]
	v_mfma_f32_16x16x32_bf16 v[104:107], v[176:179], v[200:203], v[104:107]
	v_mfma_f32_16x16x32_bf16 v[68:71], v[168:171], v[224:227], v[68:71]
	v_mfma_f32_16x16x32_bf16 v[64:67], v[176:179], v[224:227], v[64:67]
	v_mfma_f32_16x16x32_bf16 v[148:151], v[172:175], v[188:191], v[148:151]
	v_mfma_f32_16x16x32_bf16 v[144:147], v[180:183], v[188:191], v[144:147]
	v_mfma_f32_16x16x32_bf16 v[124:127], v[172:175], v[196:199], v[124:127]
	v_mfma_f32_16x16x32_bf16 v[120:123], v[180:183], v[196:199], v[120:123]
	v_mfma_f32_16x16x32_bf16 v[108:111], v[172:175], v[204:207], v[108:111]
	v_mfma_f32_16x16x32_bf16 v[104:107], v[180:183], v[204:207], v[104:107]
	v_mfma_f32_16x16x32_bf16 v[68:71], v[172:175], v[228:231], v[68:71]
	v_mfma_f32_16x16x32_bf16 v[64:67], v[180:183], v[228:231], v[64:67]
	s_barrier
	ds_read_b128 v[184:187], v223 offset:49152
	ds_read_b128 v[188:191], v223 offset:50176
	ds_read_b128 v[192:195], v223 offset:51200
	ds_read_b128 v[196:199], v223 offset:52224
	ds_read_b128 v[200:203], v223 offset:53248
	ds_read_b128 v[204:207], v223 offset:54272
	ds_read_b128 v[224:227], v223 offset:55296
	ds_read_b128 v[228:231], v223 offset:56320
	s_or_b32 s13, s12, 0x4000
	s_mov_b32 m0, s34
	s_nop 0
	buffer_load_dwordx4 v220, s[48:51], s13 offen lds
	s_add_i32 s12, s12, 0x84000
	s_mov_b32 m0, s84
	s_nop 0
	buffer_load_dwordx4 v221, s[48:51], s13 offen lds
	s_nop 0
	s_mov_b32 m0, s87
	s_nop 0
	buffer_load_dwordx4 v220, s[48:51], s12 offen lds
	s_nop 0
	s_mov_b32 m0, s88
	s_nop 0
	buffer_load_dwordx4 v221, s[48:51], s12 offen lds
	s_nop 0
	s_mov_b32 m0, s85
	s_nop 0
	buffer_load_dwordx4 v220, s[64:67], s11 offen lds
	s_nop 0
	s_mov_b32 m0, s86
	s_nop 0
	buffer_load_dwordx4 v221, s[64:67], s11 offen lds
	s_waitcnt vmcnt(8)
	s_waitcnt lgkmcnt(0)
	s_barrier
	s_waitcnt lgkmcnt(7)
	v_mfma_f32_16x16x32_bf16 v[60:63], v[128:131], v[184:187], v[60:63]
	v_mfma_f32_16x16x32_bf16 v[56:59], v[152:155], v[184:187], v[56:59]
	s_waitcnt lgkmcnt(5)
	v_mfma_f32_16x16x32_bf16 v[44:47], v[128:131], v[192:195], v[44:47]
	v_mfma_f32_16x16x32_bf16 v[40:43], v[152:155], v[192:195], v[40:43]
	s_waitcnt lgkmcnt(3)
	v_mfma_f32_16x16x32_bf16 v[28:31], v[128:131], v[200:203], v[28:31]
	v_mfma_f32_16x16x32_bf16 v[24:27], v[152:155], v[200:203], v[24:27]
	s_waitcnt lgkmcnt(1)
	v_mfma_f32_16x16x32_bf16 v[12:15], v[128:131], v[224:227], v[12:15]
	v_mfma_f32_16x16x32_bf16 v[8:11], v[152:155], v[224:227], v[8:11]
	v_mfma_f32_16x16x32_bf16 v[60:63], v[140:143], v[188:191], v[60:63]
	v_mfma_f32_16x16x32_bf16 v[56:59], v[156:159], v[188:191], v[56:59]
	v_mfma_f32_16x16x32_bf16 v[44:47], v[140:143], v[196:199], v[44:47]
	v_mfma_f32_16x16x32_bf16 v[40:43], v[156:159], v[196:199], v[40:43]
	v_mfma_f32_16x16x32_bf16 v[28:31], v[140:143], v[204:207], v[28:31]
	v_mfma_f32_16x16x32_bf16 v[24:27], v[156:159], v[204:207], v[24:27]
	s_waitcnt lgkmcnt(0)
	v_mfma_f32_16x16x32_bf16 v[12:15], v[140:143], v[228:231], v[12:15]
	v_mfma_f32_16x16x32_bf16 v[8:11], v[156:159], v[228:231], v[8:11]
	v_mfma_f32_16x16x32_bf16 v[52:55], v[168:171], v[184:187], v[52:55]
	v_mfma_f32_16x16x32_bf16 v[48:51], v[176:179], v[184:187], v[48:51]
	v_mfma_f32_16x16x32_bf16 v[36:39], v[168:171], v[192:195], v[36:39]
	v_mfma_f32_16x16x32_bf16 v[32:35], v[176:179], v[192:195], v[32:35]
	v_mfma_f32_16x16x32_bf16 v[20:23], v[168:171], v[200:203], v[20:23]
	v_mfma_f32_16x16x32_bf16 v[16:19], v[176:179], v[200:203], v[16:19]
	v_mfma_f32_16x16x32_bf16 v[4:7], v[168:171], v[224:227], v[4:7]
	v_mfma_f32_16x16x32_bf16 v[0:3], v[176:179], v[224:227], v[0:3]
	v_mfma_f32_16x16x32_bf16 v[52:55], v[172:175], v[188:191], v[52:55]
	v_mfma_f32_16x16x32_bf16 v[48:51], v[180:183], v[188:191], v[48:51]
	v_mfma_f32_16x16x32_bf16 v[36:39], v[172:175], v[196:199], v[36:39]
	v_mfma_f32_16x16x32_bf16 v[32:35], v[180:183], v[196:199], v[32:35]
	v_mfma_f32_16x16x32_bf16 v[20:23], v[172:175], v[204:207], v[20:23]
	v_mfma_f32_16x16x32_bf16 v[16:19], v[180:183], v[204:207], v[16:19]
	v_mfma_f32_16x16x32_bf16 v[4:7], v[172:175], v[228:231], v[4:7]
	v_mfma_f32_16x16x32_bf16 v[0:3], v[180:183], v[228:231], v[0:3]
	s_barrier
	s_add_i32 s10, s10, 2
	s_add_i32 s8, s8, 0x8000
	s_add_i32 s9, s9, 0x8000
	s_branch .LBB0_691

.LBB0_794:
	s_lshl_b32 s48, s45, 20
	s_and_b64 s[4:5], s[38:39], exec
	s_cselect_b32 s4, s48, s37
	s_lshl_b32 s49, s44, 20
	s_and_b64 s[52:53], s[38:39], exec
	s_cselect_b32 s5, s49, s51
	s_add_i32 s37, s37, 0x84000
	s_add_i32 s51, s51, 0x8000
	s_mov_b32 s52, -2
	s_cmp_eq_u32 s43, 1
	s_cbranch_scc0 .Lpeel_p5
	v_add_u32_e32 v164, 0x10000, v168
	ds_read_b128 v[152:155], v164
	ds_read_b128 v[156:159], v164 offset:1024
	ds_read_b128 v[160:163], v164 offset:2048
	ds_read_b128 v[170:173], v164 offset:3072
	v_add_u32_e32 v164, 0x14000, v168
	ds_read_b128 v[174:177], v164
	ds_read_b128 v[178:181], v164 offset:1024
	ds_read_b128 v[182:185], v164 offset:2048
	ds_read_b128 v[186:189], v164 offset:3072
	s_add_i32 s53, s37, 0xfff84000
	s_cmp_eq_u32 s52, 28
	s_cselect_b32 s56, s4, s53
	s_cselect_b32 s55, s5, s51
	s_or_b32 s53, s56, 0x4000
	ds_read_b128 v[190:193], v169
	ds_read_b128 v[194:197], v169 offset:1024
	ds_read_b128 v[198:201], v169 offset:2048
	ds_read_b128 v[202:205], v169 offset:3072
	ds_read_b128 v[220:223], v169 offset:4096
	ds_read_b128 v[224:227], v169 offset:5120
	ds_read_b128 v[228:231], v169 offset:6144
	ds_read_b128 v[240:243], v169 offset:7168
	s_mov_b32 m0, s41
	s_nop 0
	buffer_load_dwordx4 v166, s[24:27], s37 offen lds
	s_nop 0
	s_mov_b32 m0, s42
	s_nop 0
	buffer_load_dwordx4 v167, s[24:27], s37 offen lds
	s_waitcnt vmcnt(8)
	s_waitcnt lgkmcnt(0)
	s_barrier
	s_waitcnt lgkmcnt(7)
	v_mfma_f32_16x16x32_bf16 v[148:151], v[152:155], v[190:193], 0
	v_mfma_f32_16x16x32_bf16 v[140:143], v[160:163], v[190:193], 0
	s_waitcnt lgkmcnt(5)
	v_mfma_f32_16x16x32_bf16 v[132:135], v[152:155], v[198:201], 0
	v_mfma_f32_16x16x32_bf16 v[124:127], v[160:163], v[198:201], 0
	s_waitcnt lgkmcnt(3)
	v_mfma_f32_16x16x32_bf16 v[116:119], v[152:155], v[220:223], 0
	v_mfma_f32_16x16x32_bf16 v[108:111], v[160:163], v[220:223], 0
	s_waitcnt lgkmcnt(1)
	v_mfma_f32_16x16x32_bf16 v[76:79], v[152:155], v[228:231], 0
	v_mfma_f32_16x16x32_bf16 v[68:71], v[160:163], v[228:231], 0
	v_mfma_f32_16x16x32_bf16 v[148:151], v[156:159], v[194:197], v[148:151]
	v_mfma_f32_16x16x32_bf16 v[140:143], v[170:173], v[194:197], v[140:143]
	v_mfma_f32_16x16x32_bf16 v[132:135], v[156:159], v[202:205], v[132:135]
	v_mfma_f32_16x16x32_bf16 v[124:127], v[170:173], v[202:205], v[124:127]
	v_mfma_f32_16x16x32_bf16 v[116:119], v[156:159], v[224:227], v[116:119]
	v_mfma_f32_16x16x32_bf16 v[108:111], v[170:173], v[224:227], v[108:111]
	s_waitcnt lgkmcnt(0)
	v_mfma_f32_16x16x32_bf16 v[76:79], v[156:159], v[240:243], v[76:79]
	v_mfma_f32_16x16x32_bf16 v[68:71], v[170:173], v[240:243], v[68:71]
	v_mfma_f32_16x16x32_bf16 v[144:147], v[174:177], v[190:193], 0
	v_mfma_f32_16x16x32_bf16 v[136:139], v[182:185], v[190:193], 0
	v_mfma_f32_16x16x32_bf16 v[128:131], v[174:177], v[198:201], 0
	v_mfma_f32_16x16x32_bf16 v[120:123], v[182:185], v[198:201], 0
	v_mfma_f32_16x16x32_bf16 v[112:115], v[174:177], v[220:223], 0
	v_mfma_f32_16x16x32_bf16 v[104:107], v[182:185], v[220:223], 0
	v_mfma_f32_16x16x32_bf16 v[72:75], v[174:177], v[228:231], 0
	v_mfma_f32_16x16x32_bf16 v[64:67], v[182:185], v[228:231], 0
	v_mfma_f32_16x16x32_bf16 v[144:147], v[178:181], v[194:197], v[144:147]
	v_mfma_f32_16x16x32_bf16 v[136:139], v[186:189], v[194:197], v[136:139]
	v_mfma_f32_16x16x32_bf16 v[128:131], v[178:181], v[202:205], v[128:131]
	v_mfma_f32_16x16x32_bf16 v[120:123], v[186:189], v[202:205], v[120:123]
	v_mfma_f32_16x16x32_bf16 v[112:115], v[178:181], v[224:227], v[112:115]
	v_mfma_f32_16x16x32_bf16 v[104:107], v[186:189], v[224:227], v[104:107]
	v_mfma_f32_16x16x32_bf16 v[72:75], v[178:181], v[240:243], v[72:75]
	v_mfma_f32_16x16x32_bf16 v[64:67], v[186:189], v[240:243], v[64:67]
	s_barrier
	ds_read_b128 v[190:193], v169 offset:16384
	ds_read_b128 v[194:197], v169 offset:17408
	ds_read_b128 v[198:201], v169 offset:18432
	ds_read_b128 v[202:205], v169 offset:19456
	ds_read_b128 v[220:223], v169 offset:20480
	ds_read_b128 v[224:227], v169 offset:21504
	ds_read_b128 v[228:231], v169 offset:22528
	ds_read_b128 v[240:243], v169 offset:23552
	s_mov_b32 m0, s7
	s_nop 0
	buffer_load_dwordx4 v166, s[28:31], s55 offen lds
	s_add_i32 s57, s55, 0x80000
	s_mov_b32 m0, s8
	s_nop 0
	buffer_load_dwordx4 v167, s[28:31], s55 offen lds
	s_nop 0
	s_mov_b32 m0, s9
	s_nop 0
	buffer_load_dwordx4 v166, s[28:31], s57 offen lds
	s_nop 0
	s_mov_b32 m0, s10
	s_nop 0
	buffer_load_dwordx4 v167, s[28:31], s57 offen lds
	s_nop 0
	s_mov_b32 m0, s6
	s_nop 0
	buffer_load_dwordx4 v166, s[24:27], s56 offen lds
	s_nop 0
	s_mov_b32 m0, s11
	s_nop 0
	buffer_load_dwordx4 v167, s[24:27], s56 offen lds
	s_waitcnt vmcnt(8)
	s_waitcnt lgkmcnt(0)
	s_barrier
	s_waitcnt lgkmcnt(7)
	v_mfma_f32_16x16x32_bf16 v[60:63], v[152:155], v[190:193], 0
	v_mfma_f32_16x16x32_bf16 v[52:55], v[160:163], v[190:193], 0
	s_waitcnt lgkmcnt(5)
	v_mfma_f32_16x16x32_bf16 v[44:47], v[152:155], v[198:201], 0
	v_mfma_f32_16x16x32_bf16 v[36:39], v[160:163], v[198:201], 0
	s_waitcnt lgkmcnt(3)
	v_mfma_f32_16x16x32_bf16 v[28:31], v[152:155], v[220:223], 0
	v_mfma_f32_16x16x32_bf16 v[20:23], v[160:163], v[220:223], 0
	s_waitcnt lgkmcnt(1)
	v_mfma_f32_16x16x32_bf16 v[12:15], v[152:155], v[228:231], 0
	v_mfma_f32_16x16x32_bf16 v[4:7], v[160:163], v[228:231], 0
	v_mfma_f32_16x16x32_bf16 v[60:63], v[156:159], v[194:197], v[60:63]
	v_mfma_f32_16x16x32_bf16 v[52:55], v[170:173], v[194:197], v[52:55]
	v_mfma_f32_16x16x32_bf16 v[44:47], v[156:159], v[202:205], v[44:47]
	v_mfma_f32_16x16x32_bf16 v[36:39], v[170:173], v[202:205], v[36:39]
	v_mfma_f32_16x16x32_bf16 v[28:31], v[156:159], v[224:227], v[28:31]
	v_mfma_f32_16x16x32_bf16 v[20:23], v[170:173], v[224:227], v[20:23]
	s_waitcnt lgkmcnt(0)
	v_mfma_f32_16x16x32_bf16 v[12:15], v[156:159], v[240:243], v[12:15]
	v_mfma_f32_16x16x32_bf16 v[4:7], v[170:173], v[240:243], v[4:7]
	v_mfma_f32_16x16x32_bf16 v[56:59], v[174:177], v[190:193], 0
	v_mfma_f32_16x16x32_bf16 v[48:51], v[182:185], v[190:193], 0
	v_mfma_f32_16x16x32_bf16 v[40:43], v[174:177], v[198:201], 0
	v_mfma_f32_16x16x32_bf16 v[32:35], v[182:185], v[198:201], 0
	v_mfma_f32_16x16x32_bf16 v[24:27], v[174:177], v[220:223], 0
	v_mfma_f32_16x16x32_bf16 v[16:19], v[182:185], v[220:223], 0
	v_mfma_f32_16x16x32_bf16 v[8:11], v[174:177], v[228:231], 0
	v_mfma_f32_16x16x32_bf16 v[0:3], v[182:185], v[228:231], 0
	v_mfma_f32_16x16x32_bf16 v[56:59], v[178:181], v[194:197], v[56:59]
	v_mfma_f32_16x16x32_bf16 v[48:51], v[186:189], v[194:197], v[48:51]
	v_mfma_f32_16x16x32_bf16 v[40:43], v[178:181], v[202:205], v[40:43]
	v_mfma_f32_16x16x32_bf16 v[32:35], v[186:189], v[202:205], v[32:35]
	v_mfma_f32_16x16x32_bf16 v[24:27], v[178:181], v[224:227], v[24:27]
	v_mfma_f32_16x16x32_bf16 v[16:19], v[186:189], v[224:227], v[16:19]
	v_mfma_f32_16x16x32_bf16 v[8:11], v[178:181], v[240:243], v[8:11]
	v_mfma_f32_16x16x32_bf16 v[0:3], v[186:189], v[240:243], v[0:3]
	s_barrier
	v_add_u32_e32 v164, 0x18000, v168
	ds_read_b128 v[152:155], v164
	ds_read_b128 v[156:159], v164 offset:1024
	ds_read_b128 v[160:163], v164 offset:2048
	ds_read_b128 v[170:173], v164 offset:3072
	v_add_u32_e32 v164, 0x1c000, v168
	ds_read_b128 v[174:177], v164
	ds_read_b128 v[178:181], v164 offset:1024
	ds_read_b128 v[182:185], v164 offset:2048
	ds_read_b128 v[186:189], v164 offset:3072
	ds_read_b128 v[190:193], v169 offset:32768
	ds_read_b128 v[194:197], v169 offset:33792
	ds_read_b128 v[198:201], v169 offset:34816
	ds_read_b128 v[202:205], v169 offset:35840
	ds_read_b128 v[220:223], v169 offset:36864
	ds_read_b128 v[224:227], v169 offset:37888
	ds_read_b128 v[228:231], v169 offset:38912
	ds_read_b128 v[240:243], v169 offset:39936
	s_add_i32 s56, s56, 0x80000
	s_mov_b32 m0, s12
	s_nop 0
	buffer_load_dwordx4 v166, s[24:27], s56 offen lds
	s_nop 0
	s_mov_b32 m0, s13
	s_nop 0
	buffer_load_dwordx4 v167, s[24:27], s56 offen lds
	s_waitcnt vmcnt(8)
	s_waitcnt lgkmcnt(0)
	s_barrier
	s_waitcnt lgkmcnt(7)
	v_mfma_f32_16x16x32_bf16 v[148:151], v[152:155], v[190:193], v[148:151]
	v_mfma_f32_16x16x32_bf16 v[140:143], v[160:163], v[190:193], v[140:143]
	s_waitcnt lgkmcnt(5)
	v_mfma_f32_16x16x32_bf16 v[132:135], v[152:155], v[198:201], v[132:135]
	v_mfma_f32_16x16x32_bf16 v[124:127], v[160:163], v[198:201], v[124:127]
	s_waitcnt lgkmcnt(3)
	v_mfma_f32_16x16x32_bf16 v[116:119], v[152:155], v[220:223], v[116:119]
	v_mfma_f32_16x16x32_bf16 v[108:111], v[160:163], v[220:223], v[108:111]
	s_waitcnt lgkmcnt(1)
	v_mfma_f32_16x16x32_bf16 v[76:79], v[152:155], v[228:231], v[76:79]
	v_mfma_f32_16x16x32_bf16 v[68:71], v[160:163], v[228:231], v[68:71]
	v_mfma_f32_16x16x32_bf16 v[148:151], v[156:159], v[194:197], v[148:151]
	v_mfma_f32_16x16x32_bf16 v[140:143], v[170:173], v[194:197], v[140:143]
	v_mfma_f32_16x16x32_bf16 v[132:135], v[156:159], v[202:205], v[132:135]
	v_mfma_f32_16x16x32_bf16 v[124:127], v[170:173], v[202:205], v[124:127]
	v_mfma_f32_16x16x32_bf16 v[116:119], v[156:159], v[224:227], v[116:119]
	v_mfma_f32_16x16x32_bf16 v[108:111], v[170:173], v[224:227], v[108:111]
	s_waitcnt lgkmcnt(0)
	v_mfma_f32_16x16x32_bf16 v[76:79], v[156:159], v[240:243], v[76:79]
	v_mfma_f32_16x16x32_bf16 v[68:71], v[170:173], v[240:243], v[68:71]
	v_mfma_f32_16x16x32_bf16 v[144:147], v[174:177], v[190:193], v[144:147]
	v_mfma_f32_16x16x32_bf16 v[136:139], v[182:185], v[190:193], v[136:139]
	v_mfma_f32_16x16x32_bf16 v[128:131], v[174:177], v[198:201], v[128:131]
	v_mfma_f32_16x16x32_bf16 v[120:123], v[182:185], v[198:201], v[120:123]
	v_mfma_f32_16x16x32_bf16 v[112:115], v[174:177], v[220:223], v[112:115]
	v_mfma_f32_16x16x32_bf16 v[104:107], v[182:185], v[220:223], v[104:107]
	v_mfma_f32_16x16x32_bf16 v[72:75], v[174:177], v[228:231], v[72:75]
	v_mfma_f32_16x16x32_bf16 v[64:67], v[182:185], v[228:231], v[64:67]
	v_mfma_f32_16x16x32_bf16 v[144:147], v[178:181], v[194:197], v[144:147]
	v_mfma_f32_16x16x32_bf16 v[136:139], v[186:189], v[194:197], v[136:139]
	v_mfma_f32_16x16x32_bf16 v[128:131], v[178:181], v[202:205], v[128:131]
	v_mfma_f32_16x16x32_bf16 v[120:123], v[186:189], v[202:205], v[120:123]
	v_mfma_f32_16x16x32_bf16 v[112:115], v[178:181], v[224:227], v[112:115]
	v_mfma_f32_16x16x32_bf16 v[104:107], v[186:189], v[224:227], v[104:107]
	v_mfma_f32_16x16x32_bf16 v[72:75], v[178:181], v[240:243], v[72:75]
	v_mfma_f32_16x16x32_bf16 v[64:67], v[186:189], v[240:243], v[64:67]
	s_barrier
	ds_read_b128 v[190:193], v169 offset:49152
	ds_read_b128 v[194:197], v169 offset:50176
	ds_read_b128 v[198:201], v169 offset:51200
	ds_read_b128 v[202:205], v169 offset:52224
	ds_read_b128 v[220:223], v169 offset:53248
	ds_read_b128 v[224:227], v169 offset:54272
	ds_read_b128 v[228:231], v169 offset:55296
	ds_read_b128 v[240:243], v169 offset:56320
	s_or_b32 s56, s55, 0x4000
	s_mov_b32 m0, s16
	s_nop 0
	buffer_load_dwordx4 v166, s[28:31], s56 offen lds
	s_add_i32 s55, s55, 0x84000
	s_mov_b32 m0, s17
	s_nop 0
	buffer_load_dwordx4 v167, s[28:31], s56 offen lds
	s_nop 0
	s_mov_b32 m0, s34
	s_nop 0
	buffer_load_dwordx4 v166, s[28:31], s55 offen lds
	s_nop 0
	s_mov_b32 m0, s40
	s_nop 0
	buffer_load_dwordx4 v167, s[28:31], s55 offen lds
	s_nop 0
	s_mov_b32 m0, s18
	s_nop 0
	buffer_load_dwordx4 v166, s[24:27], s53 offen lds
	s_nop 0
	s_mov_b32 m0, s19
	s_nop 0
	buffer_load_dwordx4 v167, s[24:27], s53 offen lds
	s_waitcnt vmcnt(8)
	s_waitcnt lgkmcnt(0)
	s_barrier
	s_waitcnt lgkmcnt(7)
	v_mfma_f32_16x16x32_bf16 v[60:63], v[152:155], v[190:193], v[60:63]
	v_mfma_f32_16x16x32_bf16 v[52:55], v[160:163], v[190:193], v[52:55]
	s_waitcnt lgkmcnt(5)
	v_mfma_f32_16x16x32_bf16 v[44:47], v[152:155], v[198:201], v[44:47]
	v_mfma_f32_16x16x32_bf16 v[36:39], v[160:163], v[198:201], v[36:39]
	s_waitcnt lgkmcnt(3)
	v_mfma_f32_16x16x32_bf16 v[28:31], v[152:155], v[220:223], v[28:31]
	v_mfma_f32_16x16x32_bf16 v[20:23], v[160:163], v[220:223], v[20:23]
	s_waitcnt lgkmcnt(1)
	v_mfma_f32_16x16x32_bf16 v[12:15], v[152:155], v[228:231], v[12:15]
	v_mfma_f32_16x16x32_bf16 v[4:7], v[160:163], v[228:231], v[4:7]
	v_mfma_f32_16x16x32_bf16 v[60:63], v[156:159], v[194:197], v[60:63]
	v_mfma_f32_16x16x32_bf16 v[52:55], v[170:173], v[194:197], v[52:55]
	v_mfma_f32_16x16x32_bf16 v[44:47], v[156:159], v[202:205], v[44:47]
	v_mfma_f32_16x16x32_bf16 v[36:39], v[170:173], v[202:205], v[36:39]
	v_mfma_f32_16x16x32_bf16 v[28:31], v[156:159], v[224:227], v[28:31]
	v_mfma_f32_16x16x32_bf16 v[20:23], v[170:173], v[224:227], v[20:23]
	s_waitcnt lgkmcnt(0)
	v_mfma_f32_16x16x32_bf16 v[12:15], v[156:159], v[240:243], v[12:15]
	v_mfma_f32_16x16x32_bf16 v[4:7], v[170:173], v[240:243], v[4:7]
	v_mfma_f32_16x16x32_bf16 v[56:59], v[174:177], v[190:193], v[56:59]
	v_mfma_f32_16x16x32_bf16 v[48:51], v[182:185], v[190:193], v[48:51]
	v_mfma_f32_16x16x32_bf16 v[40:43], v[174:177], v[198:201], v[40:43]
	v_mfma_f32_16x16x32_bf16 v[32:35], v[182:185], v[198:201], v[32:35]
	v_mfma_f32_16x16x32_bf16 v[24:27], v[174:177], v[220:223], v[24:27]
	v_mfma_f32_16x16x32_bf16 v[16:19], v[182:185], v[220:223], v[16:19]
	v_mfma_f32_16x16x32_bf16 v[8:11], v[174:177], v[228:231], v[8:11]
	v_mfma_f32_16x16x32_bf16 v[0:3], v[182:185], v[228:231], v[0:3]
	v_mfma_f32_16x16x32_bf16 v[56:59], v[178:181], v[194:197], v[56:59]
	v_mfma_f32_16x16x32_bf16 v[48:51], v[186:189], v[194:197], v[48:51]
	v_mfma_f32_16x16x32_bf16 v[40:43], v[178:181], v[202:205], v[40:43]
	v_mfma_f32_16x16x32_bf16 v[32:35], v[186:189], v[202:205], v[32:35]
	v_mfma_f32_16x16x32_bf16 v[24:27], v[178:181], v[224:227], v[24:27]
	v_mfma_f32_16x16x32_bf16 v[16:19], v[186:189], v[224:227], v[16:19]
	v_mfma_f32_16x16x32_bf16 v[8:11], v[178:181], v[240:243], v[8:11]
	v_mfma_f32_16x16x32_bf16 v[0:3], v[186:189], v[240:243], v[0:3]
	s_barrier
	s_add_i32 s52, s52, 2
	s_add_i32 s37, s37, 0x8000
	s_add_i32 s51, s51, 0x8000
	s_branch .LBB0_795

.LBB0_884:
	s_mul_i32 s92, s90, 0x2c0000
	s_and_b64 s[6:7], s[38:39], exec
	s_mul_i32 s93, s91, 0x2c0000
	s_cselect_b32 s6, s92, s8
	s_cselect_b32 s7, s93, s9
	s_add_i32 s8, s8, 0x164000
	s_add_i32 s9, s9, 0x8000
	s_mov_b32 s10, -2
	s_cmp_eq_u32 s88, 1
	s_cbranch_scc0 .Lpeel_p6
	v_add_u32_e32 v156, 0x10000, v222
	v_add_u32_e32 v180, 0x14000, v222
	ds_read_b128 v[128:131], v156
	ds_read_b128 v[140:143], v156 offset:1024
	ds_read_b128 v[152:155], v156 offset:2048
	ds_read_b128 v[156:159], v156 offset:3072
	ds_read_b128 v[168:171], v180
	ds_read_b128 v[172:175], v180 offset:1024
	ds_read_b128 v[176:179], v180 offset:2048
	ds_read_b128 v[180:183], v180 offset:3072
	s_add_i32 s11, s8, 0xffea4000
	s_cmpk_eq_i32 s10, 0x54
	s_cselect_b32 s13, s6, s11
	s_cselect_b32 s12, s7, s9
	s_or_b32 s11, s13, 0x4000
	ds_read_b128 v[184:187], v223
	ds_read_b128 v[188:191], v223 offset:1024
	ds_read_b128 v[192:195], v223 offset:2048
	ds_read_b128 v[196:199], v223 offset:3072
	ds_read_b128 v[200:203], v223 offset:4096
	ds_read_b128 v[204:207], v223 offset:5120
	ds_read_b128 v[224:227], v223 offset:6144
	ds_read_b128 v[228:231], v223 offset:7168
	s_mov_b32 m0, s87
	s_nop 0
	buffer_load_dwordx4 v220, s[20:23], s8 offen lds
	s_nop 0
	s_mov_b32 m0, s89
	s_nop 0
	buffer_load_dwordx4 v221, s[20:23], s8 offen lds
	s_waitcnt vmcnt(8)
	s_waitcnt lgkmcnt(0)
	s_barrier
	s_waitcnt lgkmcnt(7)
	v_mfma_f32_16x16x32_bf16 v[164:167], v[128:131], v[184:187], 0
	v_mfma_f32_16x16x32_bf16 v[160:163], v[152:155], v[184:187], 0
	s_waitcnt lgkmcnt(5)
	v_mfma_f32_16x16x32_bf16 v[136:139], v[128:131], v[192:195], 0
	v_mfma_f32_16x16x32_bf16 v[132:135], v[152:155], v[192:195], 0
	s_waitcnt lgkmcnt(3)
	v_mfma_f32_16x16x32_bf16 v[116:119], v[128:131], v[200:203], 0
	v_mfma_f32_16x16x32_bf16 v[112:115], v[152:155], v[200:203], 0
	s_waitcnt lgkmcnt(1)
	v_mfma_f32_16x16x32_bf16 v[76:79], v[128:131], v[224:227], 0
	v_mfma_f32_16x16x32_bf16 v[72:75], v[152:155], v[224:227], 0
	v_mfma_f32_16x16x32_bf16 v[164:167], v[140:143], v[188:191], v[164:167]
	v_mfma_f32_16x16x32_bf16 v[160:163], v[156:159], v[188:191], v[160:163]
	v_mfma_f32_16x16x32_bf16 v[136:139], v[140:143], v[196:199], v[136:139]
	v_mfma_f32_16x16x32_bf16 v[132:135], v[156:159], v[196:199], v[132:135]
	v_mfma_f32_16x16x32_bf16 v[116:119], v[140:143], v[204:207], v[116:119]
	v_mfma_f32_16x16x32_bf16 v[112:115], v[156:159], v[204:207], v[112:115]
	s_waitcnt lgkmcnt(0)
	v_mfma_f32_16x16x32_bf16 v[76:79], v[140:143], v[228:231], v[76:79]
	v_mfma_f32_16x16x32_bf16 v[72:75], v[156:159], v[228:231], v[72:75]
	v_mfma_f32_16x16x32_bf16 v[148:151], v[168:171], v[184:187], 0
	v_mfma_f32_16x16x32_bf16 v[144:147], v[176:179], v[184:187], 0
	v_mfma_f32_16x16x32_bf16 v[124:127], v[168:171], v[192:195], 0
	v_mfma_f32_16x16x32_bf16 v[120:123], v[176:179], v[192:195], 0
	v_mfma_f32_16x16x32_bf16 v[108:111], v[168:171], v[200:203], 0
	v_mfma_f32_16x16x32_bf16 v[104:107], v[176:179], v[200:203], 0
	v_mfma_f32_16x16x32_bf16 v[68:71], v[168:171], v[224:227], 0
	v_mfma_f32_16x16x32_bf16 v[64:67], v[176:179], v[224:227], 0
	v_mfma_f32_16x16x32_bf16 v[148:151], v[172:175], v[188:191], v[148:151]
	v_mfma_f32_16x16x32_bf16 v[144:147], v[180:183], v[188:191], v[144:147]
	v_mfma_f32_16x16x32_bf16 v[124:127], v[172:175], v[196:199], v[124:127]
	v_mfma_f32_16x16x32_bf16 v[120:123], v[180:183], v[196:199], v[120:123]
	v_mfma_f32_16x16x32_bf16 v[108:111], v[172:175], v[204:207], v[108:111]
	v_mfma_f32_16x16x32_bf16 v[104:107], v[180:183], v[204:207], v[104:107]
	v_mfma_f32_16x16x32_bf16 v[68:71], v[172:175], v[228:231], v[68:71]
	v_mfma_f32_16x16x32_bf16 v[64:67], v[180:183], v[228:231], v[64:67]
	s_barrier
	ds_read_b128 v[184:187], v223 offset:16384
	ds_read_b128 v[188:191], v223 offset:17408
	ds_read_b128 v[192:195], v223 offset:18432
	ds_read_b128 v[196:199], v223 offset:19456
	ds_read_b128 v[200:203], v223 offset:20480
	ds_read_b128 v[204:207], v223 offset:21504
	ds_read_b128 v[224:227], v223 offset:22528
	ds_read_b128 v[228:231], v223 offset:23552
	s_mov_b32 m0, s51
	s_nop 0
	buffer_load_dwordx4 v220, s[52:55], s12 offen lds
	s_add_i32 s14, s12, 0x160000
	s_mov_b32 m0, s74
	s_nop 0
	buffer_load_dwordx4 v221, s[52:55], s12 offen lds
	s_nop 0
	s_mov_b32 m0, s75
	s_nop 0
	buffer_load_dwordx4 v220, s[52:55], s14 offen lds
	s_nop 0
	s_mov_b32 m0, s76
	s_nop 0
	buffer_load_dwordx4 v221, s[52:55], s14 offen lds
	s_nop 0
	s_mov_b32 m0, s31
	s_nop 0
	buffer_load_dwordx4 v220, s[20:23], s13 offen lds
	s_nop 0
	s_mov_b32 m0, s77
	s_nop 0
	buffer_load_dwordx4 v221, s[20:23], s13 offen lds
	s_waitcnt vmcnt(8)
	s_waitcnt lgkmcnt(0)
	s_barrier
	s_waitcnt lgkmcnt(7)
	v_mfma_f32_16x16x32_bf16 v[60:63], v[128:131], v[184:187], 0
	v_mfma_f32_16x16x32_bf16 v[56:59], v[152:155], v[184:187], 0
	s_waitcnt lgkmcnt(5)
	v_mfma_f32_16x16x32_bf16 v[44:47], v[128:131], v[192:195], 0
	v_mfma_f32_16x16x32_bf16 v[40:43], v[152:155], v[192:195], 0
	s_waitcnt lgkmcnt(3)
	v_mfma_f32_16x16x32_bf16 v[28:31], v[128:131], v[200:203], 0
	v_mfma_f32_16x16x32_bf16 v[24:27], v[152:155], v[200:203], 0
	s_waitcnt lgkmcnt(1)
	v_mfma_f32_16x16x32_bf16 v[12:15], v[128:131], v[224:227], 0
	v_mfma_f32_16x16x32_bf16 v[8:11], v[152:155], v[224:227], 0
	v_mfma_f32_16x16x32_bf16 v[60:63], v[140:143], v[188:191], v[60:63]
	v_mfma_f32_16x16x32_bf16 v[56:59], v[156:159], v[188:191], v[56:59]
	v_mfma_f32_16x16x32_bf16 v[44:47], v[140:143], v[196:199], v[44:47]
	v_mfma_f32_16x16x32_bf16 v[40:43], v[156:159], v[196:199], v[40:43]
	v_mfma_f32_16x16x32_bf16 v[28:31], v[140:143], v[204:207], v[28:31]
	v_mfma_f32_16x16x32_bf16 v[24:27], v[156:159], v[204:207], v[24:27]
	s_waitcnt lgkmcnt(0)
	v_mfma_f32_16x16x32_bf16 v[12:15], v[140:143], v[228:231], v[12:15]
	v_mfma_f32_16x16x32_bf16 v[8:11], v[156:159], v[228:231], v[8:11]
	v_mfma_f32_16x16x32_bf16 v[52:55], v[168:171], v[184:187], 0
	v_mfma_f32_16x16x32_bf16 v[48:51], v[176:179], v[184:187], 0
	v_mfma_f32_16x16x32_bf16 v[36:39], v[168:171], v[192:195], 0
	v_mfma_f32_16x16x32_bf16 v[32:35], v[176:179], v[192:195], 0
	v_mfma_f32_16x16x32_bf16 v[20:23], v[168:171], v[200:203], 0
	v_mfma_f32_16x16x32_bf16 v[16:19], v[176:179], v[200:203], 0
	v_mfma_f32_16x16x32_bf16 v[4:7], v[168:171], v[224:227], 0
	v_mfma_f32_16x16x32_bf16 v[0:3], v[176:179], v[224:227], 0
	v_mfma_f32_16x16x32_bf16 v[52:55], v[172:175], v[188:191], v[52:55]
	v_mfma_f32_16x16x32_bf16 v[48:51], v[180:183], v[188:191], v[48:51]
	v_mfma_f32_16x16x32_bf16 v[36:39], v[172:175], v[196:199], v[36:39]
	v_mfma_f32_16x16x32_bf16 v[32:35], v[180:183], v[196:199], v[32:35]
	v_mfma_f32_16x16x32_bf16 v[20:23], v[172:175], v[204:207], v[20:23]
	v_mfma_f32_16x16x32_bf16 v[16:19], v[180:183], v[204:207], v[16:19]
	v_mfma_f32_16x16x32_bf16 v[4:7], v[172:175], v[228:231], v[4:7]
	v_mfma_f32_16x16x32_bf16 v[0:3], v[180:183], v[228:231], v[0:3]
	s_barrier
	v_add_u32_e32 v156, 0x18000, v222
	v_add_u32_e32 v180, 0x1c000, v222
	ds_read_b128 v[128:131], v156
	ds_read_b128 v[140:143], v156 offset:1024
	ds_read_b128 v[152:155], v156 offset:2048
	ds_read_b128 v[156:159], v156 offset:3072
	ds_read_b128 v[168:171], v180
	ds_read_b128 v[172:175], v180 offset:1024
	ds_read_b128 v[176:179], v180 offset:2048
	ds_read_b128 v[180:183], v180 offset:3072
	ds_read_b128 v[184:187], v223 offset:32768
	ds_read_b128 v[188:191], v223 offset:33792
	ds_read_b128 v[192:195], v223 offset:34816
	ds_read_b128 v[196:199], v223 offset:35840
	ds_read_b128 v[200:203], v223 offset:36864
	ds_read_b128 v[204:207], v223 offset:37888
	ds_read_b128 v[224:227], v223 offset:38912
	ds_read_b128 v[228:231], v223 offset:39936
	s_add_i32 s13, s13, 0x160000
	s_mov_b32 m0, s78
	s_nop 0
	buffer_load_dwordx4 v220, s[20:23], s13 offen lds
	s_nop 0
	s_mov_b32 m0, s79
	s_nop 0
	buffer_load_dwordx4 v221, s[20:23], s13 offen lds
	s_waitcnt vmcnt(8)
	s_waitcnt lgkmcnt(0)
	s_barrier
	s_waitcnt lgkmcnt(7)
	v_mfma_f32_16x16x32_bf16 v[164:167], v[128:131], v[184:187], v[164:167]
	v_mfma_f32_16x16x32_bf16 v[160:163], v[152:155], v[184:187], v[160:163]
	s_waitcnt lgkmcnt(5)
	v_mfma_f32_16x16x32_bf16 v[136:139], v[128:131], v[192:195], v[136:139]
	v_mfma_f32_16x16x32_bf16 v[132:135], v[152:155], v[192:195], v[132:135]
	s_waitcnt lgkmcnt(3)
	v_mfma_f32_16x16x32_bf16 v[116:119], v[128:131], v[200:203], v[116:119]
	v_mfma_f32_16x16x32_bf16 v[112:115], v[152:155], v[200:203], v[112:115]
	s_waitcnt lgkmcnt(1)
	v_mfma_f32_16x16x32_bf16 v[76:79], v[128:131], v[224:227], v[76:79]
	v_mfma_f32_16x16x32_bf16 v[72:75], v[152:155], v[224:227], v[72:75]
	v_mfma_f32_16x16x32_bf16 v[164:167], v[140:143], v[188:191], v[164:167]
	v_mfma_f32_16x16x32_bf16 v[160:163], v[156:159], v[188:191], v[160:163]
	v_mfma_f32_16x16x32_bf16 v[136:139], v[140:143], v[196:199], v[136:139]
	v_mfma_f32_16x16x32_bf16 v[132:135], v[156:159], v[196:199], v[132:135]
	v_mfma_f32_16x16x32_bf16 v[116:119], v[140:143], v[204:207], v[116:119]
	v_mfma_f32_16x16x32_bf16 v[112:115], v[156:159], v[204:207], v[112:115]
	s_waitcnt lgkmcnt(0)
	v_mfma_f32_16x16x32_bf16 v[76:79], v[140:143], v[228:231], v[76:79]
	v_mfma_f32_16x16x32_bf16 v[72:75], v[156:159], v[228:231], v[72:75]
	v_mfma_f32_16x16x32_bf16 v[148:151], v[168:171], v[184:187], v[148:151]
	v_mfma_f32_16x16x32_bf16 v[144:147], v[176:179], v[184:187], v[144:147]
	v_mfma_f32_16x16x32_bf16 v[124:127], v[168:171], v[192:195], v[124:127]
	v_mfma_f32_16x16x32_bf16 v[120:123], v[176:179], v[192:195], v[120:123]
	v_mfma_f32_16x16x32_bf16 v[108:111], v[168:171], v[200:203], v[108:111]
	v_mfma_f32_16x16x32_bf16 v[104:107], v[176:179], v[200:203], v[104:107]
	v_mfma_f32_16x16x32_bf16 v[68:71], v[168:171], v[224:227], v[68:71]
	v_mfma_f32_16x16x32_bf16 v[64:67], v[176:179], v[224:227], v[64:67]
	v_mfma_f32_16x16x32_bf16 v[148:151], v[172:175], v[188:191], v[148:151]
	v_mfma_f32_16x16x32_bf16 v[144:147], v[180:183], v[188:191], v[144:147]
	v_mfma_f32_16x16x32_bf16 v[124:127], v[172:175], v[196:199], v[124:127]
	v_mfma_f32_16x16x32_bf16 v[120:123], v[180:183], v[196:199], v[120:123]
	v_mfma_f32_16x16x32_bf16 v[108:111], v[172:175], v[204:207], v[108:111]
	v_mfma_f32_16x16x32_bf16 v[104:107], v[180:183], v[204:207], v[104:107]
	v_mfma_f32_16x16x32_bf16 v[68:71], v[172:175], v[228:231], v[68:71]
	v_mfma_f32_16x16x32_bf16 v[64:67], v[180:183], v[228:231], v[64:67]
	s_barrier
	ds_read_b128 v[184:187], v223 offset:49152
	ds_read_b128 v[188:191], v223 offset:50176
	ds_read_b128 v[192:195], v223 offset:51200
	ds_read_b128 v[196:199], v223 offset:52224
	ds_read_b128 v[200:203], v223 offset:53248
	ds_read_b128 v[204:207], v223 offset:54272
	ds_read_b128 v[224:227], v223 offset:55296
	ds_read_b128 v[228:231], v223 offset:56320
	s_or_b32 s13, s12, 0x4000
	s_mov_b32 m0, s34
	s_nop 0
	buffer_load_dwordx4 v220, s[52:55], s13 offen lds
	s_add_i32 s12, s12, 0x164000
	s_mov_b32 m0, s82
	s_nop 0
	buffer_load_dwordx4 v221, s[52:55], s13 offen lds
	s_nop 0
	s_mov_b32 m0, s85
	s_nop 0
	buffer_load_dwordx4 v220, s[52:55], s12 offen lds
	s_nop 0
	s_mov_b32 m0, s86
	s_nop 0
	buffer_load_dwordx4 v221, s[52:55], s12 offen lds
	s_nop 0
	s_mov_b32 m0, s83
	s_nop 0
	buffer_load_dwordx4 v220, s[20:23], s11 offen lds
	s_nop 0
	s_mov_b32 m0, s84
	s_nop 0
	buffer_load_dwordx4 v221, s[20:23], s11 offen lds
	s_waitcnt vmcnt(8)
	s_waitcnt lgkmcnt(0)
	s_barrier
	s_waitcnt lgkmcnt(7)
	v_mfma_f32_16x16x32_bf16 v[60:63], v[128:131], v[184:187], v[60:63]
	v_mfma_f32_16x16x32_bf16 v[56:59], v[152:155], v[184:187], v[56:59]
	s_waitcnt lgkmcnt(5)
	v_mfma_f32_16x16x32_bf16 v[44:47], v[128:131], v[192:195], v[44:47]
	v_mfma_f32_16x16x32_bf16 v[40:43], v[152:155], v[192:195], v[40:43]
	s_waitcnt lgkmcnt(3)
	v_mfma_f32_16x16x32_bf16 v[28:31], v[128:131], v[200:203], v[28:31]
	v_mfma_f32_16x16x32_bf16 v[24:27], v[152:155], v[200:203], v[24:27]
	s_waitcnt lgkmcnt(1)
	v_mfma_f32_16x16x32_bf16 v[12:15], v[128:131], v[224:227], v[12:15]
	v_mfma_f32_16x16x32_bf16 v[8:11], v[152:155], v[224:227], v[8:11]
	v_mfma_f32_16x16x32_bf16 v[60:63], v[140:143], v[188:191], v[60:63]
	v_mfma_f32_16x16x32_bf16 v[56:59], v[156:159], v[188:191], v[56:59]
	v_mfma_f32_16x16x32_bf16 v[44:47], v[140:143], v[196:199], v[44:47]
	v_mfma_f32_16x16x32_bf16 v[40:43], v[156:159], v[196:199], v[40:43]
	v_mfma_f32_16x16x32_bf16 v[28:31], v[140:143], v[204:207], v[28:31]
	v_mfma_f32_16x16x32_bf16 v[24:27], v[156:159], v[204:207], v[24:27]
	s_waitcnt lgkmcnt(0)
	v_mfma_f32_16x16x32_bf16 v[12:15], v[140:143], v[228:231], v[12:15]
	v_mfma_f32_16x16x32_bf16 v[8:11], v[156:159], v[228:231], v[8:11]
	v_mfma_f32_16x16x32_bf16 v[52:55], v[168:171], v[184:187], v[52:55]
	v_mfma_f32_16x16x32_bf16 v[48:51], v[176:179], v[184:187], v[48:51]
	v_mfma_f32_16x16x32_bf16 v[36:39], v[168:171], v[192:195], v[36:39]
	v_mfma_f32_16x16x32_bf16 v[32:35], v[176:179], v[192:195], v[32:35]
	v_mfma_f32_16x16x32_bf16 v[20:23], v[168:171], v[200:203], v[20:23]
	v_mfma_f32_16x16x32_bf16 v[16:19], v[176:179], v[200:203], v[16:19]
	v_mfma_f32_16x16x32_bf16 v[4:7], v[168:171], v[224:227], v[4:7]
	v_mfma_f32_16x16x32_bf16 v[0:3], v[176:179], v[224:227], v[0:3]
	v_mfma_f32_16x16x32_bf16 v[52:55], v[172:175], v[188:191], v[52:55]
	v_mfma_f32_16x16x32_bf16 v[48:51], v[180:183], v[188:191], v[48:51]
	v_mfma_f32_16x16x32_bf16 v[36:39], v[172:175], v[196:199], v[36:39]
	v_mfma_f32_16x16x32_bf16 v[32:35], v[180:183], v[196:199], v[32:35]
	v_mfma_f32_16x16x32_bf16 v[20:23], v[172:175], v[204:207], v[20:23]
	v_mfma_f32_16x16x32_bf16 v[16:19], v[180:183], v[204:207], v[16:19]
	v_mfma_f32_16x16x32_bf16 v[4:7], v[172:175], v[228:231], v[4:7]
	v_mfma_f32_16x16x32_bf16 v[0:3], v[180:183], v[228:231], v[0:3]
	s_barrier
	s_add_i32 s10, s10, 2
	s_add_i32 s8, s8, 0x8000
	s_add_i32 s9, s9, 0x8000
	s_branch .LBB0_885
